# init row pass: nt (non-temporal) hint on the once-read f32 input loads
# speedup vs baseline: 1.0127x; 1.0127x over previous
.LBB0_207:
	s_waitcnt lgkmcnt(0)
	global_load_dwordx4 v[14:17], v[4:5], off offset:-3072 nt
	global_load_dwordx4 v[18:21], v[4:5], off offset:-2048 nt
	global_load_dwordx4 v[22:25], v[4:5], off offset:-1024 nt
	global_load_dwordx4 v[26:29], v[4:5], off nt
	s_waitcnt vmcnt(0)
	v_mul_f32_e32 v30, v15, v15
	v_mul_f32_e32 v31, v19, v19
	v_mul_f32_e32 v32, v23, v23
	v_fmac_f32_e32 v30, v14, v14
	v_fmac_f32_e32 v31, v18, v18
	v_mul_f32_e32 v33, v27, v27
	v_fmac_f32_e32 v32, v22, v22
	v_fmac_f32_e32 v30, v16, v16
	v_fmac_f32_e32 v31, v20, v20
	v_fmac_f32_e32 v33, v26, v26
	v_fmac_f32_e32 v32, v24, v24
	v_fmac_f32_e32 v30, v17, v17
	v_fmac_f32_e32 v31, v21, v21
	v_fmac_f32_e32 v33, v28, v28
	v_fmac_f32_e32 v32, v25, v25
	v_add_f32_e32 v30, v30, v31
	v_fmac_f32_e32 v33, v29, v29
	v_add_f32_e32 v30, v30, v32
	v_add_f32_e32 v30, v30, v33
	v_mov_b32_e32 v100, v30
	v_mov_b32_e32 v101, v30
	v_cvt_pk_bf16_f32 v14, v14, v15
	v_cvt_pk_bf16_f32 v15, v16, v17
	v_permlane32_swap_b32_e32 v100, v101
	v_lshl_add_u64 v[30:31], s[2:3], 0, v[2:3]
	v_add_co_u32_e32 v30, vcc, s11, v30
	v_add_f32_e32 v102, v100, v101
	v_mov_b32_e32 v103, v102
	v_addc_co_u32_e32 v31, vcc, 0, v31, vcc
	global_store_dwordx2 v[30:31], v[14:15], off
	v_permlane16_swap_b32_e32 v102, v103
	v_cvt_pk_bf16_f32 v14, v18, v19
	v_cvt_pk_bf16_f32 v15, v20, v21
	v_add_f32_e32 v104, v102, v103
	global_store_dwordx2 v[30:31], v[14:15], off offset:512
	v_cvt_pk_bf16_f32 v16, v22, v23
	v_cvt_pk_bf16_f32 v17, v24, v25
	v_add_f32_dpp v105, v104, v104 row_shl:8 row_mask:0xf bank_mask:0xf
	global_store_dwordx2 v[30:31], v[16:17], off offset:1024
	v_cvt_pk_bf16_f32 v16, v26, v27
	v_cvt_pk_bf16_f32 v17, v28, v29
	v_add_f32_dpp v106, v105, v105 row_shl:4 row_mask:0xf bank_mask:0xf
	global_store_dwordx2 v[30:31], v[16:17], off offset:1536
	s_nop 1
	v_add_f32_dpp v107, v106, v106 row_shl:2 row_mask:0xf bank_mask:0xf
	s_nop 1
	v_add_f32_dpp v14, v107, v107 row_shl:1 row_mask:0xf bank_mask:0xf
	s_and_saveexec_b64 s[20:21], s[0:1]
	s_cbranch_execz .LBB0_206
	v_fmamk_f32 v14, v14, 0x3a800000, v13
	v_mul_f32_e32 v15, 0x4b800000, v14
	v_cmp_gt_f32_e32 vcc, s22, v14
	s_nop 1
	v_cndmask_b32_e32 v14, v14, v15, vcc
	v_rsq_f32_e32 v16, v14
	v_lshl_add_u64 v[14:15], s[2:3], 0, v[0:1]
	v_mul_f32_e32 v17, 0x45800000, v16
	v_cndmask_b32_e32 v16, v16, v17, vcc
	global_store_dword v[14:15], v16, off
	s_branch .LBB0_206
